# MLA: waves 4-7 issue their tile writes in front of their 1st PV MFMA (barrier still behind the 2nd)
# baseline (speedup 1.0000x reference)
; __device__ __forceinline__ void finishSM9(f32x16& p0, f32x16& p1, float alpha, float& l_reg, v8i32& p8) {
; #pragma unroll
;   for (int r = 0; r < 16; ++r) { p0[r] = __builtin_amdgcn_exp2f(p0[r]); p1[r] = __builtin_amdgcn_exp2f(p1[r]); }
;   float ps = 0;
; #pragma unroll
;   for (int r = 0; r < 16; ++r) ps += p0[r];
; #pragma unroll
;   for (int r = 0; r < 16; ++r) ps += p1[r];
;   { auto rr = __builtin_amdgcn_permlane32_swap(__float_as_uint(ps), __float_as_uint(ps), false, false);
;     ps = __uint_as_float(rr[0]) + __uint_as_float(rr[1]); }
;   l_reg = l_reg * alpha + ps;
; #pragma unroll
;   for (int g = 0; g < 4; ++g) {
;     int w = __builtin_amdgcn_cvt_pk_fp8_f32(p0[4 * g], p0[4 * g + 1], 0, false); p8[g] = __builtin_amdgcn_cvt_pk_fp8_f32(p0[4 * g + 2], p0[4 * g + 3], w, true);
;     int u = __builtin_amdgcn_cvt_pk_fp8_f32(p1[4 * g], p1[4 * g + 1], 0, false); p8[4 + g] = __builtin_amdgcn_cvt_pk_fp8_f32(p1[4 * g + 2], p1[4 * g + 3], u, true); }
; }
; __device__ __forceinline__ void pv8(f32x16* o, const char* Vt, const v8i32 p8, int r32, int hi) {
;   const int sw = (r32 >> 2) & 3, a0 = r32 * 64 + (((hi * 2) ^ sw) << 4), a1 = r32 * 64 + (((hi * 2 + 1) ^ sw) << 4);
; #pragma unroll
;   for (int d0 = 0; d0 < 4; ++d0) {
;     const v8i32 vf = cat8(*reinterpret_cast<const v4i32*>(Vt + d0 * 2048 + a0), *reinterpret_cast<const v4i32*>(Vt + d0 * 2048 + a1));
;     o[d0] = __builtin_amdgcn_mfma_scale_f32_32x32x64_f8f6f4(p8, vf, o[d0], 0, 0, 0, 127, 0, 127); }
; }
; __device__ __forceinline__ void qkt9(f32x16& p0, f32x16& p1, const char* Kn, const char* Kr, const v8i32* qf, const float init, int r32, int hi) {
; #pragma unroll
;   for (int r = 0; r < 16; ++r) { p0[r] = init; p1[r] = init; }
; #pragma unroll
;   for (int s = 0; s < 2; ++s) { const int c0 = s * 4 + hi * 2;
;     const v8i32 a0 = cat8(*reinterpret_cast<const v4i32*>(Kn + KN8SW(r32, c0)), *reinterpret_cast<const v4i32*>(Kn + KN8SW(r32, c0 + 1)));
;     const v8i32 a1 = cat8(*reinterpret_cast<const v4i32*>(Kn + 4096 + KN8SW(r32, c0)), *reinterpret_cast<const v4i32*>(Kn + 4096 + KN8SW(r32, c0 + 1)));
;     p0 = __builtin_amdgcn_mfma_scale_f32_32x32x64_f8f6f4(a0, qf[s], p0, 0, 0, 0, 127, 0, 124);
;     p1 = __builtin_amdgcn_mfma_scale_f32_32x32x64_f8f6f4(a1, qf[s], p1, 0, 0, 0, 127, 0, 124); }
;   { const int c0 = hi * 2;
.Lmla_stag_loop:
	ds_read_b128 v[114:117], v215 offset:24576
	ds_read_b128 v[118:121], v216 offset:24576
	ds_read_b128 v[222:225], v215 offset:28672
	ds_read_b128 v[226:229], v216 offset:28672
	v_exp_f32_e32 v0, v82
	v_exp_f32_e32 v177, v83
	v_exp_f32_e32 v179, v84
	v_exp_f32_e32 v254, v85
	v_add_f32_e32 v219, v0, v177
	v_cvt_pk_fp8_f32 v246, v0, v177
	v_add_f32_e32 v219, v179, v219
	v_add_f32_e32 v219, v254, v219
	v_cvt_pk_fp8_f32 v246, v179, v254 op_sel:[0,0,1]
	s_waitcnt lgkmcnt(2)
	v_mfma_scale_f32_32x32x64_f8f6f4 v[114:129], v[114:121], v[146:153], v[230:245], v194, v193 op_sel_hi:[0,0,0]
	v_exp_f32_e32 v0, v86
	v_exp_f32_e32 v177, v87
	v_exp_f32_e32 v179, v88
	v_exp_f32_e32 v254, v89
	v_add_f32_e32 v219, v0, v219
	v_add_f32_e32 v219, v177, v219
	v_cvt_pk_fp8_f32 v247, v0, v177
	v_add_f32_e32 v219, v179, v219
	v_add_f32_e32 v219, v254, v219
	v_cvt_pk_fp8_f32 v247, v179, v254 op_sel:[0,0,1]
	ds_read_b128 v[82:85], v213 offset:24576
	ds_read_b128 v[86:89], v214 offset:24576
	s_waitcnt lgkmcnt(2)
	v_mfma_scale_f32_32x32x64_f8f6f4 v[98:113], v[222:229], v[146:153], v[230:245], v194, v193 op_sel_hi:[0,0,0]
	ds_read_b128 v[222:225], v213 offset:28672
	ds_read_b128 v[226:229], v214 offset:28672
	v_exp_f32_e32 v0, v90
	v_exp_f32_e32 v177, v91
	v_exp_f32_e32 v179, v92
	v_exp_f32_e32 v254, v93
	v_add_f32_e32 v219, v0, v219
	v_add_f32_e32 v219, v177, v219
	v_cvt_pk_fp8_f32 v248, v0, v177
	v_add_f32_e32 v219, v179, v219
	v_add_f32_e32 v219, v254, v219
	v_cvt_pk_fp8_f32 v248, v179, v254 op_sel:[0,0,1]
	v_exp_f32_e32 v0, v94
	v_exp_f32_e32 v177, v95
	v_exp_f32_e32 v179, v96
	v_exp_f32_e32 v254, v97
	v_add_f32_e32 v219, v0, v219
	v_add_f32_e32 v219, v177, v219
	v_cvt_pk_fp8_f32 v249, v0, v177
	v_add_f32_e32 v219, v179, v219
	v_add_f32_e32 v219, v254, v219
	v_cvt_pk_fp8_f32 v249, v179, v254 op_sel:[0,0,1]
	ds_read_b128 v[90:93], v185 offset:36864
	ds_read_b128 v[94:97], v186 offset:36864
	s_waitcnt lgkmcnt(4)
	v_mfma_scale_f32_32x32x64_f8f6f4 v[114:129], v[82:89], v[138:145], v[114:129], v194, v193 op_sel_hi:[0,0,0]
	v_exp_f32_e32 v0, v66
	v_exp_f32_e32 v177, v67
	v_exp_f32_e32 v179, v68
	v_exp_f32_e32 v254, v69
	v_add_f32_e32 v219, v0, v219
	v_add_f32_e32 v219, v177, v219
	v_cvt_pk_fp8_f32 v250, v0, v177
	v_add_f32_e32 v219, v179, v219
	v_add_f32_e32 v219, v254, v219
	v_cvt_pk_fp8_f32 v250, v179, v254 op_sel:[0,0,1]
	s_waitcnt lgkmcnt(2)
	v_mfma_scale_f32_32x32x64_f8f6f4 v[98:113], v[222:229], v[138:145], v[98:113], v194, v193 op_sel_hi:[0,0,0]
	ds_read_b128 v[222:225], v185 offset:38912
	ds_read_b128 v[226:229], v186 offset:38912
	v_exp_f32_e32 v0, v70
	v_exp_f32_e32 v177, v71
	v_exp_f32_e32 v179, v72
	v_exp_f32_e32 v254, v73
	v_add_f32_e32 v219, v0, v219
	v_add_f32_e32 v219, v177, v219
	v_cvt_pk_fp8_f32 v251, v0, v177
	v_add_f32_e32 v219, v179, v219
	v_add_f32_e32 v219, v254, v219
	v_cvt_pk_fp8_f32 v251, v179, v254 op_sel:[0,0,1]
	v_exp_f32_e32 v0, v74
	v_exp_f32_e32 v177, v75
	v_exp_f32_e32 v179, v76
	v_exp_f32_e32 v254, v77
	v_add_f32_e32 v219, v0, v219
	v_add_f32_e32 v219, v177, v219
	v_cvt_pk_fp8_f32 v252, v0, v177
	v_add_f32_e32 v219, v179, v219
	v_add_f32_e32 v219, v254, v219
	v_cvt_pk_fp8_f32 v252, v179, v254 op_sel:[0,0,1]
	s_waitcnt lgkmcnt(2)
	v_mfma_scale_f32_32x32x64_f8f6f4 v[114:129], v[90:97], v[130:137], v[114:129], v194, v193 op_sel_hi:[0,0,0]
	v_exp_f32_e32 v0, v78
	v_exp_f32_e32 v177, v79
	v_exp_f32_e32 v179, v80
	v_exp_f32_e32 v254, v81
	v_add_f32_e32 v219, v0, v219
	v_add_f32_e32 v219, v177, v219
	v_cvt_pk_fp8_f32 v253, v0, v177
	v_add_f32_e32 v219, v179, v219
	v_add_f32_e32 v219, v254, v219
	v_cvt_pk_fp8_f32 v253, v179, v254 op_sel:[0,0,1]
	ds_read_b128 v[90:93], v185 offset:0
	ds_read_b128 v[94:97], v186 offset:0
	ds_read_b128 v[82:85], v185 offset:2048
	ds_read_b128 v[86:89], v186 offset:2048
	ds_read_b128 v[74:77], v185 offset:4096
	ds_read_b128 v[78:81], v186 offset:4096
	ds_read_b128 v[66:69], v185 offset:6144
	ds_read_b128 v[70:73], v186 offset:6144
	s_waitcnt lgkmcnt(8)
	v_mfma_scale_f32_32x32x64_f8f6f4 v[98:113], v[222:229], v[130:137], v[98:113], v194, v193 op_sel_hi:[0,0,0]
	v_mov_b32_e32 v0, v219
	s_nop 1
	v_permlane32_swap_b32_e32 v219, v0
	v_add_f32_e32 v219, v219, v0
	v_fma_f32 v209, v209, v218, v219
	v_max_f32_e32 v177, v114, v115
	v_max3_f32 v177, v177, v116, v117
	v_max3_f32 v177, v177, v118, v119
	v_max3_f32 v177, v177, v120, v121
	v_max3_f32 v177, v177, v122, v123
	v_max3_f32 v177, v177, v124, v125
	v_max3_f32 v177, v177, v126, v127
	v_max3_f32 v177, v177, v128, v129
	s_waitcnt vmcnt(0)
	ds_write_b128 v210, v[158:161] offset:43008
	ds_write_b128 v211, v[162:165] offset:51200
	s_waitcnt lgkmcnt(8)
	v_mfma_scale_f32_32x32x64_f8f6f4 v[50:65], v[246:253], v[90:97], v[50:65], v194, v194 op_sel_hi:[0,0,0]
	s_waitcnt lgkmcnt(6)
	v_mfma_scale_f32_32x32x64_f8f6f4 v[34:49], v[246:253], v[82:89], v[34:49], v194, v194 op_sel_hi:[0,0,0]
	s_waitcnt lgkmcnt(0)
	s_barrier
	s_waitcnt lgkmcnt(2)
	v_mfma_scale_f32_32x32x64_f8f6f4 v[18:33], v[246:253], v[74:81], v[18:33], v194, v194 op_sel_hi:[0,0,0]
	global_load_dwordx4 v[158:161], v176, s[18:19]
	global_load_dwordx4 v[162:165], v178, s[16:17]
	v_add_u32_e32 v176, 0x2000, v176
	v_add_u32_e32 v178, 0x20000, v178
	s_waitcnt lgkmcnt(0)
	v_mfma_scale_f32_32x32x64_f8f6f4 v[2:17], v[246:253], v[66:73], v[2:17], v194, v194 op_sel_hi:[0,0,0]
	v_max_f32_e32 v0, v98, v99
	v_max3_f32 v0, v0, v100, v101
	v_max3_f32 v0, v0, v102, v103
	v_max3_f32 v0, v0, v104, v105
	v_max3_f32 v0, v0, v106, v107
	v_max3_f32 v0, v0, v108, v109
	v_max3_f32 v0, v0, v110, v111
	v_max3_f32 v0, v0, v112, v113
	v_max_f32_e32 v177, v177, v0
	v_mov_b32_e32 v0, v177
	v_mov_b32_e32 v221, 1.0
	s_nop 0
	v_permlane32_swap_b32_e32 v177, v0
	v_max_f32_e32 v177, v177, v0
	v_cmp_ge_f32_e32 vcc, s90, v177
	s_cmp_eq_u64 vcc, exec
	s_cbranch_scc0 .Lmla_s0_newmax
; __device__ __forceinline__ void finishSM9(f32x16& p0, f32x16& p1, float alpha, float& l_reg, v8i32& p8) {
; #pragma unroll
;   for (int r = 0; r < 16; ++r) { p0[r] = __builtin_amdgcn_exp2f(p0[r]); p1[r] = __builtin_amdgcn_exp2f(p1[r]); }
;   float ps = 0;
; #pragma unroll
;   for (int r = 0; r < 16; ++r) ps += p0[r];
; #pragma unroll
;   for (int r = 0; r < 16; ++r) ps += p1[r];
;   { auto rr = __builtin_amdgcn_permlane32_swap(__float_as_uint(ps), __float_as_uint(ps), false, false);
;     ps = __uint_as_float(rr[0]) + __uint_as_float(rr[1]); }
;   l_reg = l_reg * alpha + ps;
; #pragma unroll
;   for (int g = 0; g < 4; ++g) {
;     int w = __builtin_amdgcn_cvt_pk_fp8_f32(p0[4 * g], p0[4 * g + 1], 0, false); p8[g] = __builtin_amdgcn_cvt_pk_fp8_f32(p0[4 * g + 2], p0[4 * g + 3], w, true);
;     int u = __builtin_amdgcn_cvt_pk_fp8_f32(p1[4 * g], p1[4 * g + 1], 0, false); p8[4 + g] = __builtin_amdgcn_cvt_pk_fp8_f32(p1[4 * g + 2], p1[4 * g + 3], u, true); }
; }
; __device__ __forceinline__ void pv8(f32x16* o, const char* Vt, const v8i32 p8, int r32, int hi) {
;   const int sw = (r32 >> 2) & 3, a0 = r32 * 64 + (((hi * 2) ^ sw) << 4), a1 = r32 * 64 + (((hi * 2 + 1) ^ sw) << 4);
; #pragma unroll
;   for (int d0 = 0; d0 < 4; ++d0) {
;     const v8i32 vf = cat8(*reinterpret_cast<const v4i32*>(Vt + d0 * 2048 + a0), *reinterpret_cast<const v4i32*>(Vt + d0 * 2048 + a1));
;     o[d0] = __builtin_amdgcn_mfma_scale_f32_32x32x64_f8f6f4(p8, vf, o[d0], 0, 0, 0, 127, 0, 127); }
; }
; __device__ __forceinline__ void qkt9(f32x16& p0, f32x16& p1, const char* Kn, const char* Kr, const v8i32* qf, const float init, int r32, int hi) {
; #pragma unroll
;   for (int r = 0; r < 16; ++r) { p0[r] = init; p1[r] = init; }
; #pragma unroll
;   for (int s = 0; s < 2; ++s) { const int c0 = s * 4 + hi * 2;
;     const v8i32 a0 = cat8(*reinterpret_cast<const v4i32*>(Kn + KN8SW(r32, c0)), *reinterpret_cast<const v4i32*>(Kn + KN8SW(r32, c0 + 1)));
;     const v8i32 a1 = cat8(*reinterpret_cast<const v4i32*>(Kn + 4096 + KN8SW(r32, c0)), *reinterpret_cast<const v4i32*>(Kn + 4096 + KN8SW(r32, c0 + 1)));
;     p0 = __builtin_amdgcn_mfma_scale_f32_32x32x64_f8f6f4(a0, qf[s], p0, 0, 0, 0, 127, 0, 124);
;     p1 = __builtin_amdgcn_mfma_scale_f32_32x32x64_f8f6f4(a1, qf[s], p1, 0, 0, 0, 127, 0, 124); }
;   { const int c0 = hi * 2;
.Lmla_s0_cont:
	ds_read_b128 v[82:85], v215 offset:51200
	ds_read_b128 v[86:89], v216 offset:51200
	ds_read_b128 v[222:225], v215 offset:55296
	ds_read_b128 v[226:229], v216 offset:55296
	v_exp_f32_e32 v0, v114
	v_exp_f32_e32 v177, v115
	v_exp_f32_e32 v179, v116
	v_exp_f32_e32 v254, v117
	v_add_f32_e32 v219, v0, v177
	v_cvt_pk_fp8_f32 v246, v0, v177
	v_add_f32_e32 v219, v179, v219
	v_add_f32_e32 v219, v254, v219
	v_cvt_pk_fp8_f32 v246, v179, v254 op_sel:[0,0,1]
	s_waitcnt lgkmcnt(2)
	v_mfma_scale_f32_32x32x64_f8f6f4 v[82:97], v[82:89], v[146:153], v[230:245], v194, v193 op_sel_hi:[0,0,0]
	v_exp_f32_e32 v0, v118
	v_exp_f32_e32 v177, v119
	v_exp_f32_e32 v179, v120
	v_exp_f32_e32 v254, v121
	v_add_f32_e32 v219, v0, v219
	v_add_f32_e32 v219, v177, v219
	v_cvt_pk_fp8_f32 v247, v0, v177
	v_add_f32_e32 v219, v179, v219
	v_add_f32_e32 v219, v254, v219
	v_cvt_pk_fp8_f32 v247, v179, v254 op_sel:[0,0,1]
	ds_read_b128 v[114:117], v213 offset:51200
	ds_read_b128 v[118:121], v214 offset:51200
	s_waitcnt lgkmcnt(2)
	v_mfma_scale_f32_32x32x64_f8f6f4 v[66:81], v[222:229], v[146:153], v[230:245], v194, v193 op_sel_hi:[0,0,0]
	ds_read_b128 v[222:225], v213 offset:55296
	ds_read_b128 v[226:229], v214 offset:55296
	v_exp_f32_e32 v0, v122
	v_exp_f32_e32 v177, v123
	v_exp_f32_e32 v179, v124
	v_exp_f32_e32 v254, v125
	v_add_f32_e32 v219, v0, v219
	v_add_f32_e32 v219, v177, v219
	v_cvt_pk_fp8_f32 v248, v0, v177
	v_add_f32_e32 v219, v179, v219
	v_add_f32_e32 v219, v254, v219
	v_cvt_pk_fp8_f32 v248, v179, v254 op_sel:[0,0,1]
	v_exp_f32_e32 v0, v126
	v_exp_f32_e32 v177, v127
	v_exp_f32_e32 v179, v128
	v_exp_f32_e32 v254, v129
	v_add_f32_e32 v219, v0, v219
	v_add_f32_e32 v219, v177, v219
	v_cvt_pk_fp8_f32 v249, v0, v177
	v_add_f32_e32 v219, v179, v219
	v_add_f32_e32 v219, v254, v219
	v_cvt_pk_fp8_f32 v249, v179, v254 op_sel:[0,0,1]
	ds_read_b128 v[122:125], v185 offset:59392
	ds_read_b128 v[126:129], v186 offset:59392
	s_waitcnt lgkmcnt(4)
	v_mfma_scale_f32_32x32x64_f8f6f4 v[82:97], v[114:121], v[138:145], v[82:97], v194, v193 op_sel_hi:[0,0,0]
	v_exp_f32_e32 v0, v98
	v_exp_f32_e32 v177, v99
	v_exp_f32_e32 v179, v100
	v_exp_f32_e32 v254, v101
	v_add_f32_e32 v219, v0, v219
	v_add_f32_e32 v219, v177, v219
	v_cvt_pk_fp8_f32 v250, v0, v177
	v_add_f32_e32 v219, v179, v219
	v_add_f32_e32 v219, v254, v219
	v_cvt_pk_fp8_f32 v250, v179, v254 op_sel:[0,0,1]
	s_waitcnt lgkmcnt(2)
	v_mfma_scale_f32_32x32x64_f8f6f4 v[66:81], v[222:229], v[138:145], v[66:81], v194, v193 op_sel_hi:[0,0,0]
	ds_read_b128 v[222:225], v185 offset:61440
	ds_read_b128 v[226:229], v186 offset:61440
	v_exp_f32_e32 v0, v102
	v_exp_f32_e32 v177, v103
	v_exp_f32_e32 v179, v104
	v_exp_f32_e32 v254, v105
	v_add_f32_e32 v219, v0, v219
	v_add_f32_e32 v219, v177, v219
	v_cvt_pk_fp8_f32 v251, v0, v177
	v_add_f32_e32 v219, v179, v219
	v_add_f32_e32 v219, v254, v219
	v_cvt_pk_fp8_f32 v251, v179, v254 op_sel:[0,0,1]
	v_exp_f32_e32 v0, v106
	v_exp_f32_e32 v177, v107
	v_exp_f32_e32 v179, v108
	v_exp_f32_e32 v254, v109
	v_add_f32_e32 v219, v0, v219
	v_add_f32_e32 v219, v177, v219
	v_cvt_pk_fp8_f32 v252, v0, v177
	v_add_f32_e32 v219, v179, v219
	v_add_f32_e32 v219, v254, v219
	v_cvt_pk_fp8_f32 v252, v179, v254 op_sel:[0,0,1]
	s_waitcnt lgkmcnt(2)
	v_mfma_scale_f32_32x32x64_f8f6f4 v[82:97], v[122:129], v[130:137], v[82:97], v194, v193 op_sel_hi:[0,0,0]
	v_exp_f32_e32 v0, v110
	v_exp_f32_e32 v177, v111
	v_exp_f32_e32 v179, v112
	v_exp_f32_e32 v254, v113
	v_add_f32_e32 v219, v0, v219
	v_add_f32_e32 v219, v177, v219
	v_cvt_pk_fp8_f32 v253, v0, v177
	v_add_f32_e32 v219, v179, v219
	v_add_f32_e32 v219, v254, v219
	v_cvt_pk_fp8_f32 v253, v179, v254 op_sel:[0,0,1]
	ds_read_b128 v[122:125], v185 offset:8192
	ds_read_b128 v[126:129], v186 offset:8192
	ds_read_b128 v[114:117], v185 offset:10240
	ds_read_b128 v[118:121], v186 offset:10240
	ds_read_b128 v[106:109], v185 offset:12288
	ds_read_b128 v[110:113], v186 offset:12288
	ds_read_b128 v[98:101], v185 offset:14336
	ds_read_b128 v[102:105], v186 offset:14336
	s_waitcnt lgkmcnt(8)
	v_mfma_scale_f32_32x32x64_f8f6f4 v[66:81], v[222:229], v[130:137], v[66:81], v194, v193 op_sel_hi:[0,0,0]
	v_mov_b32_e32 v0, v219
	s_nop 1
	v_permlane32_swap_b32_e32 v219, v0
	v_add_f32_e32 v219, v219, v0
	v_fma_f32 v209, v209, v221, v219
	v_max_f32_e32 v177, v82, v83
	v_max3_f32 v177, v177, v84, v85
	v_max3_f32 v177, v177, v86, v87
	v_max3_f32 v177, v177, v88, v89
	v_max3_f32 v177, v177, v90, v91
	v_max3_f32 v177, v177, v92, v93
	v_max3_f32 v177, v177, v94, v95
	v_max3_f32 v177, v177, v96, v97
	s_waitcnt vmcnt(0)
	ds_write_b128 v210, v[158:161]
	ds_write_b128 v211, v[162:165] offset:16384
	s_waitcnt lgkmcnt(8)
	v_mfma_scale_f32_32x32x64_f8f6f4 v[50:65], v[246:253], v[122:129], v[50:65], v194, v194 op_sel_hi:[0,0,0]
	s_waitcnt lgkmcnt(6)
	v_mfma_scale_f32_32x32x64_f8f6f4 v[34:49], v[246:253], v[114:121], v[34:49], v194, v194 op_sel_hi:[0,0,0]
	s_waitcnt lgkmcnt(0)
	s_barrier
	s_waitcnt lgkmcnt(2)
	v_mfma_scale_f32_32x32x64_f8f6f4 v[18:33], v[246:253], v[106:113], v[18:33], v194, v194 op_sel_hi:[0,0,0]
	global_load_dwordx4 v[158:161], v176, s[18:19]
	global_load_dwordx4 v[162:165], v178, s[16:17]
	v_add_u32_e32 v176, 0x2000, v176
	v_add_u32_e32 v178, 0x20000, v178
	s_waitcnt lgkmcnt(0)
	v_mfma_scale_f32_32x32x64_f8f6f4 v[2:17], v[246:253], v[98:105], v[2:17], v194, v194 op_sel_hi:[0,0,0]
	v_max_f32_e32 v0, v66, v67
	v_max3_f32 v0, v0, v68, v69
	v_max3_f32 v0, v0, v70, v71
	v_max3_f32 v0, v0, v72, v73
	v_max3_f32 v0, v0, v74, v75
	v_max3_f32 v0, v0, v76, v77
	v_max3_f32 v0, v0, v78, v79
	v_max3_f32 v0, v0, v80, v81
	v_max_f32_e32 v177, v177, v0
	v_mov_b32_e32 v0, v177
	v_mov_b32_e32 v218, 1.0
	s_nop 0
	v_permlane32_swap_b32_e32 v177, v0
	v_max_f32_e32 v177, v177, v0
	v_cmp_ge_f32_e32 vcc, s90, v177
	s_cmp_eq_u64 vcc, exec
	s_cbranch_scc0 .Lmla_s1_newmax
; __device__ __forceinline__ void finishSM9(f32x16& p0, f32x16& p1, float alpha, float& l_reg, v8i32& p8) {
; #pragma unroll
;   for (int r = 0; r < 16; ++r) { p0[r] = __builtin_amdgcn_exp2f(p0[r]); p1[r] = __builtin_amdgcn_exp2f(p1[r]); }
;   float ps = 0;
; #pragma unroll
;   for (int r = 0; r < 16; ++r) ps += p0[r];
; #pragma unroll
;   for (int r = 0; r < 16; ++r) ps += p1[r];
;   { auto rr = __builtin_amdgcn_permlane32_swap(__float_as_uint(ps), __float_as_uint(ps), false, false);
;     ps = __uint_as_float(rr[0]) + __uint_as_float(rr[1]); }
;   l_reg = l_reg * alpha + ps;
; #pragma unroll
;   for (int g = 0; g < 4; ++g) {
;     int w = __builtin_amdgcn_cvt_pk_fp8_f32(p0[4 * g], p0[4 * g + 1], 0, false); p8[g] = __builtin_amdgcn_cvt_pk_fp8_f32(p0[4 * g + 2], p0[4 * g + 3], w, true);
;     int u = __builtin_amdgcn_cvt_pk_fp8_f32(p1[4 * g], p1[4 * g + 1], 0, false); p8[4 + g] = __builtin_amdgcn_cvt_pk_fp8_f32(p1[4 * g + 2], p1[4 * g + 3], u, true); }
; }
; __device__ __forceinline__ void pv8(f32x16* o, const char* Vt, const v8i32 p8, int r32, int hi) {
;   const int sw = (r32 >> 2) & 3, a0 = r32 * 64 + (((hi * 2) ^ sw) << 4), a1 = r32 * 64 + (((hi * 2 + 1) ^ sw) << 4);
; #pragma unroll
;   for (int d0 = 0; d0 < 4; ++d0) {
;     const v8i32 vf = cat8(*reinterpret_cast<const v4i32*>(Vt + d0 * 2048 + a0), *reinterpret_cast<const v4i32*>(Vt + d0 * 2048 + a1));
;     o[d0] = __builtin_amdgcn_mfma_scale_f32_32x32x64_f8f6f4(p8, vf, o[d0], 0, 0, 0, 127, 0, 127); }
; }
; __device__ __forceinline__ void qkt9(f32x16& p0, f32x16& p1, const char* Kn, const char* Kr, const v8i32* qf, const float init, int r32, int hi) {
; #pragma unroll
;   for (int r = 0; r < 16; ++r) { p0[r] = init; p1[r] = init; }
; #pragma unroll
;   for (int s = 0; s < 2; ++s) { const int c0 = s * 4 + hi * 2;
;     const v8i32 a0 = cat8(*reinterpret_cast<const v4i32*>(Kn + KN8SW(r32, c0)), *reinterpret_cast<const v4i32*>(Kn + KN8SW(r32, c0 + 1)));
;     const v8i32 a1 = cat8(*reinterpret_cast<const v4i32*>(Kn + 4096 + KN8SW(r32, c0)), *reinterpret_cast<const v4i32*>(Kn + 4096 + KN8SW(r32, c0 + 1)));
;     p0 = __builtin_amdgcn_mfma_scale_f32_32x32x64_f8f6f4(a0, qf[s], p0, 0, 0, 0, 127, 0, 124);
;     p1 = __builtin_amdgcn_mfma_scale_f32_32x32x64_f8f6f4(a1, qf[s], p1, 0, 0, 0, 127, 0, 124); }
;   { const int c0 = hi * 2;
.Lmla_s1_cont:
	ds_read_b128 v[114:117], v215 offset:16384
	ds_read_b128 v[118:121], v216 offset:16384
	ds_read_b128 v[222:225], v215 offset:20480
	ds_read_b128 v[226:229], v216 offset:20480
	v_exp_f32_e32 v0, v82
	v_exp_f32_e32 v177, v83
	v_exp_f32_e32 v179, v84
	v_exp_f32_e32 v254, v85
	v_add_f32_e32 v219, v0, v177
	v_cvt_pk_fp8_f32 v246, v0, v177
	v_add_f32_e32 v219, v179, v219
	v_add_f32_e32 v219, v254, v219
	v_cvt_pk_fp8_f32 v246, v179, v254 op_sel:[0,0,1]
	s_waitcnt lgkmcnt(2)
	v_mfma_scale_f32_32x32x64_f8f6f4 v[114:129], v[114:121], v[146:153], v[230:245], v194, v193 op_sel_hi:[0,0,0]
	v_exp_f32_e32 v0, v86
	v_exp_f32_e32 v177, v87
	v_exp_f32_e32 v179, v88
	v_exp_f32_e32 v254, v89
	v_add_f32_e32 v219, v0, v219
	v_add_f32_e32 v219, v177, v219
	v_cvt_pk_fp8_f32 v247, v0, v177
	v_add_f32_e32 v219, v179, v219
	v_add_f32_e32 v219, v254, v219
	v_cvt_pk_fp8_f32 v247, v179, v254 op_sel:[0,0,1]
	ds_read_b128 v[82:85], v213 offset:16384
	ds_read_b128 v[86:89], v214 offset:16384
	s_waitcnt lgkmcnt(2)
	v_mfma_scale_f32_32x32x64_f8f6f4 v[98:113], v[222:229], v[146:153], v[230:245], v194, v193 op_sel_hi:[0,0,0]
	ds_read_b128 v[222:225], v213 offset:20480
	ds_read_b128 v[226:229], v214 offset:20480
	v_exp_f32_e32 v0, v90
	v_exp_f32_e32 v177, v91
	v_exp_f32_e32 v179, v92
	v_exp_f32_e32 v254, v93
	v_add_f32_e32 v219, v0, v219
	v_add_f32_e32 v219, v177, v219
	v_cvt_pk_fp8_f32 v248, v0, v177
	v_add_f32_e32 v219, v179, v219
	v_add_f32_e32 v219, v254, v219
	v_cvt_pk_fp8_f32 v248, v179, v254 op_sel:[0,0,1]
	v_exp_f32_e32 v0, v94
	v_exp_f32_e32 v177, v95
	v_exp_f32_e32 v179, v96
	v_exp_f32_e32 v254, v97
	v_add_f32_e32 v219, v0, v219
	v_add_f32_e32 v219, v177, v219
	v_cvt_pk_fp8_f32 v249, v0, v177
	v_add_f32_e32 v219, v179, v219
	v_add_f32_e32 v219, v254, v219
	v_cvt_pk_fp8_f32 v249, v179, v254 op_sel:[0,0,1]
	ds_read_b128 v[90:93], v185 offset:32768
	ds_read_b128 v[94:97], v186 offset:32768
	s_waitcnt lgkmcnt(4)
	v_mfma_scale_f32_32x32x64_f8f6f4 v[114:129], v[82:89], v[138:145], v[114:129], v194, v193 op_sel_hi:[0,0,0]
	v_exp_f32_e32 v0, v66
	v_exp_f32_e32 v177, v67
	v_exp_f32_e32 v179, v68
	v_exp_f32_e32 v254, v69
	v_add_f32_e32 v219, v0, v219
	v_add_f32_e32 v219, v177, v219
	v_cvt_pk_fp8_f32 v250, v0, v177
	v_add_f32_e32 v219, v179, v219
	v_add_f32_e32 v219, v254, v219
	v_cvt_pk_fp8_f32 v250, v179, v254 op_sel:[0,0,1]
	s_waitcnt lgkmcnt(2)
	v_mfma_scale_f32_32x32x64_f8f6f4 v[98:113], v[222:229], v[138:145], v[98:113], v194, v193 op_sel_hi:[0,0,0]
	ds_read_b128 v[222:225], v185 offset:34816
	ds_read_b128 v[226:229], v186 offset:34816
	v_exp_f32_e32 v0, v70
	v_exp_f32_e32 v177, v71
	v_exp_f32_e32 v179, v72
	v_exp_f32_e32 v254, v73
	v_add_f32_e32 v219, v0, v219
	v_add_f32_e32 v219, v177, v219
	v_cvt_pk_fp8_f32 v251, v0, v177
	v_add_f32_e32 v219, v179, v219
	v_add_f32_e32 v219, v254, v219
	v_cvt_pk_fp8_f32 v251, v179, v254 op_sel:[0,0,1]
	v_exp_f32_e32 v0, v74
	v_exp_f32_e32 v177, v75
	v_exp_f32_e32 v179, v76
	v_exp_f32_e32 v254, v77
	v_add_f32_e32 v219, v0, v219
	v_add_f32_e32 v219, v177, v219
	v_cvt_pk_fp8_f32 v252, v0, v177
	v_add_f32_e32 v219, v179, v219
	v_add_f32_e32 v219, v254, v219
	v_cvt_pk_fp8_f32 v252, v179, v254 op_sel:[0,0,1]
	s_waitcnt lgkmcnt(2)
	v_mfma_scale_f32_32x32x64_f8f6f4 v[114:129], v[90:97], v[130:137], v[114:129], v194, v193 op_sel_hi:[0,0,0]
	v_exp_f32_e32 v0, v78
	v_exp_f32_e32 v177, v79
	v_exp_f32_e32 v179, v80
	v_exp_f32_e32 v254, v81
	v_add_f32_e32 v219, v0, v219
	v_add_f32_e32 v219, v177, v219
	v_cvt_pk_fp8_f32 v253, v0, v177
	v_add_f32_e32 v219, v179, v219
	v_add_f32_e32 v219, v254, v219
	v_cvt_pk_fp8_f32 v253, v179, v254 op_sel:[0,0,1]
	ds_read_b128 v[90:93], v185 offset:43008
	ds_read_b128 v[94:97], v186 offset:43008
	ds_read_b128 v[82:85], v185 offset:45056
	ds_read_b128 v[86:89], v186 offset:45056
	ds_read_b128 v[74:77], v185 offset:47104
	ds_read_b128 v[78:81], v186 offset:47104
	ds_read_b128 v[66:69], v185 offset:49152
	ds_read_b128 v[70:73], v186 offset:49152
	s_waitcnt lgkmcnt(8)
	v_mfma_scale_f32_32x32x64_f8f6f4 v[98:113], v[222:229], v[130:137], v[98:113], v194, v193 op_sel_hi:[0,0,0]
	v_mov_b32_e32 v0, v219
	s_nop 1
	v_permlane32_swap_b32_e32 v219, v0
	v_add_f32_e32 v219, v219, v0
	v_fma_f32 v209, v209, v218, v219
	v_max_f32_e32 v177, v114, v115
	v_max3_f32 v177, v177, v116, v117
	v_max3_f32 v177, v177, v118, v119
	v_max3_f32 v177, v177, v120, v121
	v_max3_f32 v177, v177, v122, v123
	v_max3_f32 v177, v177, v124, v125
	v_max3_f32 v177, v177, v126, v127
	v_max3_f32 v177, v177, v128, v129
	s_waitcnt vmcnt(0)
	ds_write_b128 v210, v[158:161] offset:8192
	ds_write_b128 v211, v[162:165] offset:24576
	s_waitcnt lgkmcnt(8)
	v_mfma_scale_f32_32x32x64_f8f6f4 v[50:65], v[246:253], v[90:97], v[50:65], v194, v194 op_sel_hi:[0,0,0]
	s_waitcnt lgkmcnt(6)
	v_mfma_scale_f32_32x32x64_f8f6f4 v[34:49], v[246:253], v[82:89], v[34:49], v194, v194 op_sel_hi:[0,0,0]
	s_waitcnt lgkmcnt(0)
	s_barrier
	s_waitcnt lgkmcnt(2)
	v_mfma_scale_f32_32x32x64_f8f6f4 v[18:33], v[246:253], v[74:81], v[18:33], v194, v194 op_sel_hi:[0,0,0]
	global_load_dwordx4 v[158:161], v176, s[18:19]
	global_load_dwordx4 v[162:165], v178, s[16:17]
	v_add_u32_e32 v176, 0x2000, v176
	v_add_u32_e32 v178, 0x20000, v178
	s_waitcnt lgkmcnt(0)
	v_mfma_scale_f32_32x32x64_f8f6f4 v[2:17], v[246:253], v[66:73], v[2:17], v194, v194 op_sel_hi:[0,0,0]
	v_max_f32_e32 v0, v98, v99
	v_max3_f32 v0, v0, v100, v101
	v_max3_f32 v0, v0, v102, v103
	v_max3_f32 v0, v0, v104, v105
	v_max3_f32 v0, v0, v106, v107
	v_max3_f32 v0, v0, v108, v109
	v_max3_f32 v0, v0, v110, v111
	v_max3_f32 v0, v0, v112, v113
	v_max_f32_e32 v177, v177, v0
	v_mov_b32_e32 v0, v177
	v_mov_b32_e32 v221, 1.0
	s_nop 0
	v_permlane32_swap_b32_e32 v177, v0
	v_max_f32_e32 v177, v177, v0
	v_cmp_ge_f32_e32 vcc, s90, v177
	s_cmp_eq_u64 vcc, exec
	s_cbranch_scc0 .Lmla_s2_newmax
; __device__ __forceinline__ void finishSM9(f32x16& p0, f32x16& p1, float alpha, float& l_reg, v8i32& p8) {
; #pragma unroll
;   for (int r = 0; r < 16; ++r) { p0[r] = __builtin_amdgcn_exp2f(p0[r]); p1[r] = __builtin_amdgcn_exp2f(p1[r]); }
;   float ps = 0;
; #pragma unroll
;   for (int r = 0; r < 16; ++r) ps += p0[r];
; #pragma unroll
;   for (int r = 0; r < 16; ++r) ps += p1[r];
;   { auto rr = __builtin_amdgcn_permlane32_swap(__float_as_uint(ps), __float_as_uint(ps), false, false);
;     ps = __uint_as_float(rr[0]) + __uint_as_float(rr[1]); }
;   l_reg = l_reg * alpha + ps;
; #pragma unroll
;   for (int g = 0; g < 4; ++g) {
;     int w = __builtin_amdgcn_cvt_pk_fp8_f32(p0[4 * g], p0[4 * g + 1], 0, false); p8[g] = __builtin_amdgcn_cvt_pk_fp8_f32(p0[4 * g + 2], p0[4 * g + 3], w, true);
;     int u = __builtin_amdgcn_cvt_pk_fp8_f32(p1[4 * g], p1[4 * g + 1], 0, false); p8[4 + g] = __builtin_amdgcn_cvt_pk_fp8_f32(p1[4 * g + 2], p1[4 * g + 3], u, true); }
; }
; __device__ __forceinline__ void pv8(f32x16* o, const char* Vt, const v8i32 p8, int r32, int hi) {
;   const int sw = (r32 >> 2) & 3, a0 = r32 * 64 + (((hi * 2) ^ sw) << 4), a1 = r32 * 64 + (((hi * 2 + 1) ^ sw) << 4);
; #pragma unroll
;   for (int d0 = 0; d0 < 4; ++d0) {
;     const v8i32 vf = cat8(*reinterpret_cast<const v4i32*>(Vt + d0 * 2048 + a0), *reinterpret_cast<const v4i32*>(Vt + d0 * 2048 + a1));
;     o[d0] = __builtin_amdgcn_mfma_scale_f32_32x32x64_f8f6f4(p8, vf, o[d0], 0, 0, 0, 127, 0, 127); }
; }
; __device__ __forceinline__ void qkt9(f32x16& p0, f32x16& p1, const char* Kn, const char* Kr, const v8i32* qf, const float init, int r32, int hi) {
; #pragma unroll
;   for (int r = 0; r < 16; ++r) { p0[r] = init; p1[r] = init; }
; #pragma unroll
;   for (int s = 0; s < 2; ++s) { const int c0 = s * 4 + hi * 2;
;     const v8i32 a0 = cat8(*reinterpret_cast<const v4i32*>(Kn + KN8SW(r32, c0)), *reinterpret_cast<const v4i32*>(Kn + KN8SW(r32, c0 + 1)));
;     const v8i32 a1 = cat8(*reinterpret_cast<const v4i32*>(Kn + 4096 + KN8SW(r32, c0)), *reinterpret_cast<const v4i32*>(Kn + 4096 + KN8SW(r32, c0 + 1)));
;     p0 = __builtin_amdgcn_mfma_scale_f32_32x32x64_f8f6f4(a0, qf[s], p0, 0, 0, 0, 127, 0, 124);
;     p1 = __builtin_amdgcn_mfma_scale_f32_32x32x64_f8f6f4(a1, qf[s], p1, 0, 0, 0, 127, 0, 124); }
;   { const int c0 = hi * 2;
.Lmla_s2_cont:
	ds_read_b128 v[82:85], v215 offset:24576
	ds_read_b128 v[86:89], v216 offset:24576
	ds_read_b128 v[222:225], v215 offset:28672
	ds_read_b128 v[226:229], v216 offset:28672
	v_exp_f32_e32 v0, v114
	v_exp_f32_e32 v177, v115
	v_exp_f32_e32 v179, v116
	v_exp_f32_e32 v254, v117
	v_add_f32_e32 v219, v0, v177
	v_cvt_pk_fp8_f32 v246, v0, v177
	v_add_f32_e32 v219, v179, v219
	v_add_f32_e32 v219, v254, v219
	v_cvt_pk_fp8_f32 v246, v179, v254 op_sel:[0,0,1]
	s_waitcnt lgkmcnt(2)
	v_mfma_scale_f32_32x32x64_f8f6f4 v[82:97], v[82:89], v[146:153], v[230:245], v194, v193 op_sel_hi:[0,0,0]
	v_exp_f32_e32 v0, v118
	v_exp_f32_e32 v177, v119
	v_exp_f32_e32 v179, v120
	v_exp_f32_e32 v254, v121
	v_add_f32_e32 v219, v0, v219
	v_add_f32_e32 v219, v177, v219
	v_cvt_pk_fp8_f32 v247, v0, v177
	v_add_f32_e32 v219, v179, v219
	v_add_f32_e32 v219, v254, v219
	v_cvt_pk_fp8_f32 v247, v179, v254 op_sel:[0,0,1]
	ds_read_b128 v[114:117], v213 offset:24576
	ds_read_b128 v[118:121], v214 offset:24576
	s_waitcnt lgkmcnt(2)
	v_mfma_scale_f32_32x32x64_f8f6f4 v[66:81], v[222:229], v[146:153], v[230:245], v194, v193 op_sel_hi:[0,0,0]
	ds_read_b128 v[222:225], v213 offset:28672
	ds_read_b128 v[226:229], v214 offset:28672
	v_exp_f32_e32 v0, v122
	v_exp_f32_e32 v177, v123
	v_exp_f32_e32 v179, v124
	v_exp_f32_e32 v254, v125
	v_add_f32_e32 v219, v0, v219
	v_add_f32_e32 v219, v177, v219
	v_cvt_pk_fp8_f32 v248, v0, v177
	v_add_f32_e32 v219, v179, v219
	v_add_f32_e32 v219, v254, v219
	v_cvt_pk_fp8_f32 v248, v179, v254 op_sel:[0,0,1]
	v_exp_f32_e32 v0, v126
	v_exp_f32_e32 v177, v127
	v_exp_f32_e32 v179, v128
	v_exp_f32_e32 v254, v129
	v_add_f32_e32 v219, v0, v219
	v_add_f32_e32 v219, v177, v219
	v_cvt_pk_fp8_f32 v249, v0, v177
	v_add_f32_e32 v219, v179, v219
	v_add_f32_e32 v219, v254, v219
	v_cvt_pk_fp8_f32 v249, v179, v254 op_sel:[0,0,1]
	ds_read_b128 v[122:125], v185 offset:36864
	ds_read_b128 v[126:129], v186 offset:36864
	s_waitcnt lgkmcnt(4)
	v_mfma_scale_f32_32x32x64_f8f6f4 v[82:97], v[114:121], v[138:145], v[82:97], v194, v193 op_sel_hi:[0,0,0]
	v_exp_f32_e32 v0, v98
	v_exp_f32_e32 v177, v99
	v_exp_f32_e32 v179, v100
	v_exp_f32_e32 v254, v101
	v_add_f32_e32 v219, v0, v219
	v_add_f32_e32 v219, v177, v219
	v_cvt_pk_fp8_f32 v250, v0, v177
	v_add_f32_e32 v219, v179, v219
	v_add_f32_e32 v219, v254, v219
	v_cvt_pk_fp8_f32 v250, v179, v254 op_sel:[0,0,1]
	s_waitcnt lgkmcnt(2)
	v_mfma_scale_f32_32x32x64_f8f6f4 v[66:81], v[222:229], v[138:145], v[66:81], v194, v193 op_sel_hi:[0,0,0]
	ds_read_b128 v[222:225], v185 offset:38912
	ds_read_b128 v[226:229], v186 offset:38912
	v_exp_f32_e32 v0, v102
	v_exp_f32_e32 v177, v103
	v_exp_f32_e32 v179, v104
	v_exp_f32_e32 v254, v105
	v_add_f32_e32 v219, v0, v219
	v_add_f32_e32 v219, v177, v219
	v_cvt_pk_fp8_f32 v251, v0, v177
	v_add_f32_e32 v219, v179, v219
	v_add_f32_e32 v219, v254, v219
	v_cvt_pk_fp8_f32 v251, v179, v254 op_sel:[0,0,1]
	v_exp_f32_e32 v0, v106
	v_exp_f32_e32 v177, v107
	v_exp_f32_e32 v179, v108
	v_exp_f32_e32 v254, v109
	v_add_f32_e32 v219, v0, v219
	v_add_f32_e32 v219, v177, v219
	v_cvt_pk_fp8_f32 v252, v0, v177
	v_add_f32_e32 v219, v179, v219
	v_add_f32_e32 v219, v254, v219
	v_cvt_pk_fp8_f32 v252, v179, v254 op_sel:[0,0,1]
	s_waitcnt lgkmcnt(2)
	v_mfma_scale_f32_32x32x64_f8f6f4 v[82:97], v[122:129], v[130:137], v[82:97], v194, v193 op_sel_hi:[0,0,0]
	v_exp_f32_e32 v0, v110
	v_exp_f32_e32 v177, v111
	v_exp_f32_e32 v179, v112
	v_exp_f32_e32 v254, v113
	v_add_f32_e32 v219, v0, v219
	v_add_f32_e32 v219, v177, v219
	v_cvt_pk_fp8_f32 v253, v0, v177
	v_add_f32_e32 v219, v179, v219
	v_add_f32_e32 v219, v254, v219
	v_cvt_pk_fp8_f32 v253, v179, v254 op_sel:[0,0,1]
	ds_read_b128 v[122:125], v185 offset:0
	ds_read_b128 v[126:129], v186 offset:0
	ds_read_b128 v[114:117], v185 offset:2048
	ds_read_b128 v[118:121], v186 offset:2048
	ds_read_b128 v[106:109], v185 offset:4096
	ds_read_b128 v[110:113], v186 offset:4096
	ds_read_b128 v[98:101], v185 offset:6144
	ds_read_b128 v[102:105], v186 offset:6144
	s_waitcnt lgkmcnt(8)
	v_mfma_scale_f32_32x32x64_f8f6f4 v[66:81], v[222:229], v[130:137], v[66:81], v194, v193 op_sel_hi:[0,0,0]
	v_mov_b32_e32 v0, v219
	s_nop 1
	v_permlane32_swap_b32_e32 v219, v0
	v_add_f32_e32 v219, v219, v0
	v_fma_f32 v209, v209, v221, v219
	v_max_f32_e32 v177, v82, v83
	v_max3_f32 v177, v177, v84, v85
	v_max3_f32 v177, v177, v86, v87
	v_max3_f32 v177, v177, v88, v89
	v_max3_f32 v177, v177, v90, v91
	v_max3_f32 v177, v177, v92, v93
	v_max3_f32 v177, v177, v94, v95
	v_max3_f32 v177, v177, v96, v97
	s_waitcnt vmcnt(0)
	ds_write_b128 v210, v[158:161] offset:43008
	ds_write_b128 v211, v[162:165] offset:51200
	s_waitcnt lgkmcnt(8)
	v_mfma_scale_f32_32x32x64_f8f6f4 v[50:65], v[246:253], v[122:129], v[50:65], v194, v194 op_sel_hi:[0,0,0]
	s_waitcnt lgkmcnt(6)
	v_mfma_scale_f32_32x32x64_f8f6f4 v[34:49], v[246:253], v[114:121], v[34:49], v194, v194 op_sel_hi:[0,0,0]
	s_waitcnt lgkmcnt(0)
	s_barrier
	s_waitcnt lgkmcnt(2)
	v_mfma_scale_f32_32x32x64_f8f6f4 v[18:33], v[246:253], v[106:113], v[18:33], v194, v194 op_sel_hi:[0,0,0]
	global_load_dwordx4 v[158:161], v176, s[18:19]
	global_load_dwordx4 v[162:165], v178, s[16:17]
	v_add_u32_e32 v176, 0x2000, v176
	v_add_u32_e32 v178, 0x20000, v178
	s_waitcnt lgkmcnt(0)
	v_mfma_scale_f32_32x32x64_f8f6f4 v[2:17], v[246:253], v[98:105], v[2:17], v194, v194 op_sel_hi:[0,0,0]
	v_max_f32_e32 v0, v66, v67
	v_max3_f32 v0, v0, v68, v69
	v_max3_f32 v0, v0, v70, v71
	v_max3_f32 v0, v0, v72, v73
	v_max3_f32 v0, v0, v74, v75
	v_max3_f32 v0, v0, v76, v77
	v_max3_f32 v0, v0, v78, v79
	v_max3_f32 v0, v0, v80, v81
	v_max_f32_e32 v177, v177, v0
	v_mov_b32_e32 v0, v177
	v_mov_b32_e32 v218, 1.0
	s_nop 0
	v_permlane32_swap_b32_e32 v177, v0
	v_max_f32_e32 v177, v177, v0
	v_cmp_ge_f32_e32 vcc, s90, v177
	s_cmp_eq_u64 vcc, exec
	s_cbranch_scc0 .Lmla_s3_newmax
; __device__ __forceinline__ void finishSM9(f32x16& p0, f32x16& p1, float alpha, float& l_reg, v8i32& p8) {
; #pragma unroll
;   for (int r = 0; r < 16; ++r) { p0[r] = __builtin_amdgcn_exp2f(p0[r]); p1[r] = __builtin_amdgcn_exp2f(p1[r]); }
;   float ps = 0;
; #pragma unroll
;   for (int r = 0; r < 16; ++r) ps += p0[r];
; #pragma unroll
;   for (int r = 0; r < 16; ++r) ps += p1[r];
;   { auto rr = __builtin_amdgcn_permlane32_swap(__float_as_uint(ps), __float_as_uint(ps), false, false);
;     ps = __uint_as_float(rr[0]) + __uint_as_float(rr[1]); }
;   l_reg = l_reg * alpha + ps;
; #pragma unroll
;   for (int g = 0; g < 4; ++g) {
;     int w = __builtin_amdgcn_cvt_pk_fp8_f32(p0[4 * g], p0[4 * g + 1], 0, false); p8[g] = __builtin_amdgcn_cvt_pk_fp8_f32(p0[4 * g + 2], p0[4 * g + 3], w, true);
;     int u = __builtin_amdgcn_cvt_pk_fp8_f32(p1[4 * g], p1[4 * g + 1], 0, false); p8[4 + g] = __builtin_amdgcn_cvt_pk_fp8_f32(p1[4 * g + 2], p1[4 * g + 3], u, true); }
; }
; __device__ __forceinline__ void pv8(f32x16* o, const char* Vt, const v8i32 p8, int r32, int hi) {
;   const int sw = (r32 >> 2) & 3, a0 = r32 * 64 + (((hi * 2) ^ sw) << 4), a1 = r32 * 64 + (((hi * 2 + 1) ^ sw) << 4);
; #pragma unroll
;   for (int d0 = 0; d0 < 4; ++d0) {
;     const v8i32 vf = cat8(*reinterpret_cast<const v4i32*>(Vt + d0 * 2048 + a0), *reinterpret_cast<const v4i32*>(Vt + d0 * 2048 + a1));
;     o[d0] = __builtin_amdgcn_mfma_scale_f32_32x32x64_f8f6f4(p8, vf, o[d0], 0, 0, 0, 127, 0, 127); }
; }
; __device__ __forceinline__ void qkt9(f32x16& p0, f32x16& p1, const char* Kn, const char* Kr, const v8i32* qf, const float init, int r32, int hi) {
; #pragma unroll
;   for (int r = 0; r < 16; ++r) { p0[r] = init; p1[r] = init; }
; #pragma unroll
;   for (int s = 0; s < 2; ++s) { const int c0 = s * 4 + hi * 2;
;     const v8i32 a0 = cat8(*reinterpret_cast<const v4i32*>(Kn + KN8SW(r32, c0)), *reinterpret_cast<const v4i32*>(Kn + KN8SW(r32, c0 + 1)));
;     const v8i32 a1 = cat8(*reinterpret_cast<const v4i32*>(Kn + 4096 + KN8SW(r32, c0)), *reinterpret_cast<const v4i32*>(Kn + 4096 + KN8SW(r32, c0 + 1)));
;     p0 = __builtin_amdgcn_mfma_scale_f32_32x32x64_f8f6f4(a0, qf[s], p0, 0, 0, 0, 127, 0, 124);
;     p1 = __builtin_amdgcn_mfma_scale_f32_32x32x64_f8f6f4(a1, qf[s], p1, 0, 0, 0, 127, 0, 124); }
;   { const int c0 = hi * 2;
.Lmla_s3_cont:
	ds_read_b128 v[114:117], v215 offset:51200
	ds_read_b128 v[118:121], v216 offset:51200
	ds_read_b128 v[222:225], v215 offset:55296
	ds_read_b128 v[226:229], v216 offset:55296
	v_exp_f32_e32 v0, v82
	v_exp_f32_e32 v177, v83
	v_exp_f32_e32 v179, v84
	v_exp_f32_e32 v254, v85
	v_add_f32_e32 v219, v0, v177
	v_cvt_pk_fp8_f32 v246, v0, v177
	v_add_f32_e32 v219, v179, v219
	v_add_f32_e32 v219, v254, v219
	v_cvt_pk_fp8_f32 v246, v179, v254 op_sel:[0,0,1]
	s_waitcnt lgkmcnt(2)
	v_mfma_scale_f32_32x32x64_f8f6f4 v[114:129], v[114:121], v[146:153], v[230:245], v194, v193 op_sel_hi:[0,0,0]
	v_exp_f32_e32 v0, v86
	v_exp_f32_e32 v177, v87
	v_exp_f32_e32 v179, v88
	v_exp_f32_e32 v254, v89
	v_add_f32_e32 v219, v0, v219
	v_add_f32_e32 v219, v177, v219
	v_cvt_pk_fp8_f32 v247, v0, v177
	v_add_f32_e32 v219, v179, v219
	v_add_f32_e32 v219, v254, v219
	v_cvt_pk_fp8_f32 v247, v179, v254 op_sel:[0,0,1]
	ds_read_b128 v[82:85], v213 offset:51200
	ds_read_b128 v[86:89], v214 offset:51200
	s_waitcnt lgkmcnt(2)
	v_mfma_scale_f32_32x32x64_f8f6f4 v[98:113], v[222:229], v[146:153], v[230:245], v194, v193 op_sel_hi:[0,0,0]
	ds_read_b128 v[222:225], v213 offset:55296
	ds_read_b128 v[226:229], v214 offset:55296
	v_exp_f32_e32 v0, v90
	v_exp_f32_e32 v177, v91
	v_exp_f32_e32 v179, v92
	v_exp_f32_e32 v254, v93
	v_add_f32_e32 v219, v0, v219
	v_add_f32_e32 v219, v177, v219
	v_cvt_pk_fp8_f32 v248, v0, v177
	v_add_f32_e32 v219, v179, v219
	v_add_f32_e32 v219, v254, v219
	v_cvt_pk_fp8_f32 v248, v179, v254 op_sel:[0,0,1]
	v_exp_f32_e32 v0, v94
	v_exp_f32_e32 v177, v95
	v_exp_f32_e32 v179, v96
	v_exp_f32_e32 v254, v97
	v_add_f32_e32 v219, v0, v219
	v_add_f32_e32 v219, v177, v219
	v_cvt_pk_fp8_f32 v249, v0, v177
	v_add_f32_e32 v219, v179, v219
	v_add_f32_e32 v219, v254, v219
	v_cvt_pk_fp8_f32 v249, v179, v254 op_sel:[0,0,1]
	ds_read_b128 v[90:93], v185 offset:59392
	ds_read_b128 v[94:97], v186 offset:59392
	s_waitcnt lgkmcnt(4)
	v_mfma_scale_f32_32x32x64_f8f6f4 v[114:129], v[82:89], v[138:145], v[114:129], v194, v193 op_sel_hi:[0,0,0]
	v_exp_f32_e32 v0, v66
	v_exp_f32_e32 v177, v67
	v_exp_f32_e32 v179, v68
	v_exp_f32_e32 v254, v69
	v_add_f32_e32 v219, v0, v219
	v_add_f32_e32 v219, v177, v219
	v_cvt_pk_fp8_f32 v250, v0, v177
	v_add_f32_e32 v219, v179, v219
	v_add_f32_e32 v219, v254, v219
	v_cvt_pk_fp8_f32 v250, v179, v254 op_sel:[0,0,1]
	s_waitcnt lgkmcnt(2)
	v_mfma_scale_f32_32x32x64_f8f6f4 v[98:113], v[222:229], v[138:145], v[98:113], v194, v193 op_sel_hi:[0,0,0]
	ds_read_b128 v[222:225], v185 offset:61440
	ds_read_b128 v[226:229], v186 offset:61440
	v_exp_f32_e32 v0, v70
	v_exp_f32_e32 v177, v71
	v_exp_f32_e32 v179, v72
	v_exp_f32_e32 v254, v73
	v_add_f32_e32 v219, v0, v219
	v_add_f32_e32 v219, v177, v219
	v_cvt_pk_fp8_f32 v251, v0, v177
	v_add_f32_e32 v219, v179, v219
	v_add_f32_e32 v219, v254, v219
	v_cvt_pk_fp8_f32 v251, v179, v254 op_sel:[0,0,1]
	v_exp_f32_e32 v0, v74
	v_exp_f32_e32 v177, v75
	v_exp_f32_e32 v179, v76
	v_exp_f32_e32 v254, v77
	v_add_f32_e32 v219, v0, v219
	v_add_f32_e32 v219, v177, v219
	v_cvt_pk_fp8_f32 v252, v0, v177
	v_add_f32_e32 v219, v179, v219
	v_add_f32_e32 v219, v254, v219
	v_cvt_pk_fp8_f32 v252, v179, v254 op_sel:[0,0,1]
	s_waitcnt lgkmcnt(2)
	v_mfma_scale_f32_32x32x64_f8f6f4 v[114:129], v[90:97], v[130:137], v[114:129], v194, v193 op_sel_hi:[0,0,0]
	v_exp_f32_e32 v0, v78
	v_exp_f32_e32 v177, v79
	v_exp_f32_e32 v179, v80
	v_exp_f32_e32 v254, v81
	v_add_f32_e32 v219, v0, v219
	v_add_f32_e32 v219, v177, v219
	v_cvt_pk_fp8_f32 v253, v0, v177
	v_add_f32_e32 v219, v179, v219
	v_add_f32_e32 v219, v254, v219
	v_cvt_pk_fp8_f32 v253, v179, v254 op_sel:[0,0,1]
	ds_read_b128 v[90:93], v185 offset:8192
	ds_read_b128 v[94:97], v186 offset:8192
	ds_read_b128 v[82:85], v185 offset:10240
	ds_read_b128 v[86:89], v186 offset:10240
	ds_read_b128 v[74:77], v185 offset:12288
	ds_read_b128 v[78:81], v186 offset:12288
	ds_read_b128 v[66:69], v185 offset:14336
	ds_read_b128 v[70:73], v186 offset:14336
	s_waitcnt lgkmcnt(8)
	v_mfma_scale_f32_32x32x64_f8f6f4 v[98:113], v[222:229], v[130:137], v[98:113], v194, v193 op_sel_hi:[0,0,0]
	v_mov_b32_e32 v0, v219
	s_nop 1
	v_permlane32_swap_b32_e32 v219, v0
	v_add_f32_e32 v219, v219, v0
	v_fma_f32 v209, v209, v218, v219
	v_max_f32_e32 v177, v114, v115
	v_max3_f32 v177, v177, v116, v117
	v_max3_f32 v177, v177, v118, v119
	v_max3_f32 v177, v177, v120, v121
	v_max3_f32 v177, v177, v122, v123
	v_max3_f32 v177, v177, v124, v125
	v_max3_f32 v177, v177, v126, v127
	v_max3_f32 v177, v177, v128, v129
	s_waitcnt vmcnt(0)
	ds_write_b128 v210, v[158:161]
	ds_write_b128 v211, v[162:165] offset:16384
	s_waitcnt lgkmcnt(8)
	v_mfma_scale_f32_32x32x64_f8f6f4 v[50:65], v[246:253], v[90:97], v[50:65], v194, v194 op_sel_hi:[0,0,0]
	s_waitcnt lgkmcnt(6)
	v_mfma_scale_f32_32x32x64_f8f6f4 v[34:49], v[246:253], v[82:89], v[34:49], v194, v194 op_sel_hi:[0,0,0]
	s_waitcnt lgkmcnt(0)
	s_barrier
	s_waitcnt lgkmcnt(2)
	v_mfma_scale_f32_32x32x64_f8f6f4 v[18:33], v[246:253], v[74:81], v[18:33], v194, v194 op_sel_hi:[0,0,0]
	global_load_dwordx4 v[158:161], v176, s[18:19]
	global_load_dwordx4 v[162:165], v178, s[16:17]
	v_add_u32_e32 v176, 0x2000, v176
	v_add_u32_e32 v178, 0x20000, v178
	s_waitcnt lgkmcnt(0)
	v_mfma_scale_f32_32x32x64_f8f6f4 v[2:17], v[246:253], v[66:73], v[2:17], v194, v194 op_sel_hi:[0,0,0]
	v_max_f32_e32 v0, v98, v99
	v_max3_f32 v0, v0, v100, v101
	v_max3_f32 v0, v0, v102, v103
	v_max3_f32 v0, v0, v104, v105
	v_max3_f32 v0, v0, v106, v107
	v_max3_f32 v0, v0, v108, v109
	v_max3_f32 v0, v0, v110, v111
	v_max3_f32 v0, v0, v112, v113
	v_max_f32_e32 v177, v177, v0
	v_mov_b32_e32 v0, v177
	v_mov_b32_e32 v221, 1.0
	s_nop 0
	v_permlane32_swap_b32_e32 v177, v0
	v_max_f32_e32 v177, v177, v0
	v_cmp_ge_f32_e32 vcc, s90, v177
	s_cmp_eq_u64 vcc, exec
	s_cbranch_scc0 .Lmla_s4_newmax
; __device__ __forceinline__ void finishSM9(f32x16& p0, f32x16& p1, float alpha, float& l_reg, v8i32& p8) {
; #pragma unroll
;   for (int r = 0; r < 16; ++r) { p0[r] = __builtin_amdgcn_exp2f(p0[r]); p1[r] = __builtin_amdgcn_exp2f(p1[r]); }
;   float ps = 0;
; #pragma unroll
;   for (int r = 0; r < 16; ++r) ps += p0[r];
; #pragma unroll
;   for (int r = 0; r < 16; ++r) ps += p1[r];
;   { auto rr = __builtin_amdgcn_permlane32_swap(__float_as_uint(ps), __float_as_uint(ps), false, false);
;     ps = __uint_as_float(rr[0]) + __uint_as_float(rr[1]); }
;   l_reg = l_reg * alpha + ps;
; #pragma unroll
;   for (int g = 0; g < 4; ++g) {
;     int w = __builtin_amdgcn_cvt_pk_fp8_f32(p0[4 * g], p0[4 * g + 1], 0, false); p8[g] = __builtin_amdgcn_cvt_pk_fp8_f32(p0[4 * g + 2], p0[4 * g + 3], w, true);
;     int u = __builtin_amdgcn_cvt_pk_fp8_f32(p1[4 * g], p1[4 * g + 1], 0, false); p8[4 + g] = __builtin_amdgcn_cvt_pk_fp8_f32(p1[4 * g + 2], p1[4 * g + 3], u, true); }
; }
; __device__ __forceinline__ void pv8(f32x16* o, const char* Vt, const v8i32 p8, int r32, int hi) {
;   const int sw = (r32 >> 2) & 3, a0 = r32 * 64 + (((hi * 2) ^ sw) << 4), a1 = r32 * 64 + (((hi * 2 + 1) ^ sw) << 4);
; #pragma unroll
;   for (int d0 = 0; d0 < 4; ++d0) {
;     const v8i32 vf = cat8(*reinterpret_cast<const v4i32*>(Vt + d0 * 2048 + a0), *reinterpret_cast<const v4i32*>(Vt + d0 * 2048 + a1));
;     o[d0] = __builtin_amdgcn_mfma_scale_f32_32x32x64_f8f6f4(p8, vf, o[d0], 0, 0, 0, 127, 0, 127); }
; }
; __device__ __forceinline__ void qkt9(f32x16& p0, f32x16& p1, const char* Kn, const char* Kr, const v8i32* qf, const float init, int r32, int hi) {
; #pragma unroll
;   for (int r = 0; r < 16; ++r) { p0[r] = init; p1[r] = init; }
; #pragma unroll
;   for (int s = 0; s < 2; ++s) { const int c0 = s * 4 + hi * 2;
;     const v8i32 a0 = cat8(*reinterpret_cast<const v4i32*>(Kn + KN8SW(r32, c0)), *reinterpret_cast<const v4i32*>(Kn + KN8SW(r32, c0 + 1)));
;     const v8i32 a1 = cat8(*reinterpret_cast<const v4i32*>(Kn + 4096 + KN8SW(r32, c0)), *reinterpret_cast<const v4i32*>(Kn + 4096 + KN8SW(r32, c0 + 1)));
;     p0 = __builtin_amdgcn_mfma_scale_f32_32x32x64_f8f6f4(a0, qf[s], p0, 0, 0, 0, 127, 0, 124);
;     p1 = __builtin_amdgcn_mfma_scale_f32_32x32x64_f8f6f4(a1, qf[s], p1, 0, 0, 0, 127, 0, 124); }
;   { const int c0 = hi * 2;
.Lmla_s4_cont:
	ds_read_b128 v[82:85], v215 offset:16384
	ds_read_b128 v[86:89], v216 offset:16384
	ds_read_b128 v[222:225], v215 offset:20480
	ds_read_b128 v[226:229], v216 offset:20480
	v_exp_f32_e32 v0, v114
	v_exp_f32_e32 v177, v115
	v_exp_f32_e32 v179, v116
	v_exp_f32_e32 v254, v117
	v_add_f32_e32 v219, v0, v177
	v_cvt_pk_fp8_f32 v246, v0, v177
	v_add_f32_e32 v219, v179, v219
	v_add_f32_e32 v219, v254, v219
	v_cvt_pk_fp8_f32 v246, v179, v254 op_sel:[0,0,1]
	s_waitcnt lgkmcnt(2)
	v_mfma_scale_f32_32x32x64_f8f6f4 v[82:97], v[82:89], v[146:153], v[230:245], v194, v193 op_sel_hi:[0,0,0]
	v_exp_f32_e32 v0, v118
	v_exp_f32_e32 v177, v119
	v_exp_f32_e32 v179, v120
	v_exp_f32_e32 v254, v121
	v_add_f32_e32 v219, v0, v219
	v_add_f32_e32 v219, v177, v219
	v_cvt_pk_fp8_f32 v247, v0, v177
	v_add_f32_e32 v219, v179, v219
	v_add_f32_e32 v219, v254, v219
	v_cvt_pk_fp8_f32 v247, v179, v254 op_sel:[0,0,1]
	ds_read_b128 v[114:117], v213 offset:16384
	ds_read_b128 v[118:121], v214 offset:16384
	s_waitcnt lgkmcnt(2)
	v_mfma_scale_f32_32x32x64_f8f6f4 v[66:81], v[222:229], v[146:153], v[230:245], v194, v193 op_sel_hi:[0,0,0]
	ds_read_b128 v[222:225], v213 offset:20480
	ds_read_b128 v[226:229], v214 offset:20480
	v_exp_f32_e32 v0, v122
	v_exp_f32_e32 v177, v123
	v_exp_f32_e32 v179, v124
	v_exp_f32_e32 v254, v125
	v_add_f32_e32 v219, v0, v219
	v_add_f32_e32 v219, v177, v219
	v_cvt_pk_fp8_f32 v248, v0, v177
	v_add_f32_e32 v219, v179, v219
	v_add_f32_e32 v219, v254, v219
	v_cvt_pk_fp8_f32 v248, v179, v254 op_sel:[0,0,1]
	v_exp_f32_e32 v0, v126
	v_exp_f32_e32 v177, v127
	v_exp_f32_e32 v179, v128
	v_exp_f32_e32 v254, v129
	v_add_f32_e32 v219, v0, v219
	v_add_f32_e32 v219, v177, v219
	v_cvt_pk_fp8_f32 v249, v0, v177
	v_add_f32_e32 v219, v179, v219
	v_add_f32_e32 v219, v254, v219
	v_cvt_pk_fp8_f32 v249, v179, v254 op_sel:[0,0,1]
	ds_read_b128 v[122:125], v185 offset:32768
	ds_read_b128 v[126:129], v186 offset:32768
	s_waitcnt lgkmcnt(4)
	v_mfma_scale_f32_32x32x64_f8f6f4 v[82:97], v[114:121], v[138:145], v[82:97], v194, v193 op_sel_hi:[0,0,0]
	v_exp_f32_e32 v0, v98
	v_exp_f32_e32 v177, v99
	v_exp_f32_e32 v179, v100
	v_exp_f32_e32 v254, v101
	v_add_f32_e32 v219, v0, v219
	v_add_f32_e32 v219, v177, v219
	v_cvt_pk_fp8_f32 v250, v0, v177
	v_add_f32_e32 v219, v179, v219
	v_add_f32_e32 v219, v254, v219
	v_cvt_pk_fp8_f32 v250, v179, v254 op_sel:[0,0,1]
	s_waitcnt lgkmcnt(2)
	v_mfma_scale_f32_32x32x64_f8f6f4 v[66:81], v[222:229], v[138:145], v[66:81], v194, v193 op_sel_hi:[0,0,0]
	ds_read_b128 v[222:225], v185 offset:34816
	ds_read_b128 v[226:229], v186 offset:34816
	v_exp_f32_e32 v0, v102
	v_exp_f32_e32 v177, v103
	v_exp_f32_e32 v179, v104
	v_exp_f32_e32 v254, v105
	v_add_f32_e32 v219, v0, v219
	v_add_f32_e32 v219, v177, v219
	v_cvt_pk_fp8_f32 v251, v0, v177
	v_add_f32_e32 v219, v179, v219
	v_add_f32_e32 v219, v254, v219
	v_cvt_pk_fp8_f32 v251, v179, v254 op_sel:[0,0,1]
	v_exp_f32_e32 v0, v106
	v_exp_f32_e32 v177, v107
	v_exp_f32_e32 v179, v108
	v_exp_f32_e32 v254, v109
	v_add_f32_e32 v219, v0, v219
	v_add_f32_e32 v219, v177, v219
	v_cvt_pk_fp8_f32 v252, v0, v177
	v_add_f32_e32 v219, v179, v219
	v_add_f32_e32 v219, v254, v219
	v_cvt_pk_fp8_f32 v252, v179, v254 op_sel:[0,0,1]
	s_waitcnt lgkmcnt(2)
	v_mfma_scale_f32_32x32x64_f8f6f4 v[82:97], v[122:129], v[130:137], v[82:97], v194, v193 op_sel_hi:[0,0,0]
	v_exp_f32_e32 v0, v110
	v_exp_f32_e32 v177, v111
	v_exp_f32_e32 v179, v112
	v_exp_f32_e32 v254, v113
	v_add_f32_e32 v219, v0, v219
	v_add_f32_e32 v219, v177, v219
	v_cvt_pk_fp8_f32 v253, v0, v177
	v_add_f32_e32 v219, v179, v219
	v_add_f32_e32 v219, v254, v219
	v_cvt_pk_fp8_f32 v253, v179, v254 op_sel:[0,0,1]
	ds_read_b128 v[122:125], v185 offset:43008
	ds_read_b128 v[126:129], v186 offset:43008
	ds_read_b128 v[114:117], v185 offset:45056
	ds_read_b128 v[118:121], v186 offset:45056
	ds_read_b128 v[106:109], v185 offset:47104
	ds_read_b128 v[110:113], v186 offset:47104
	ds_read_b128 v[98:101], v185 offset:49152
	ds_read_b128 v[102:105], v186 offset:49152
	s_waitcnt lgkmcnt(8)
	v_mfma_scale_f32_32x32x64_f8f6f4 v[66:81], v[222:229], v[130:137], v[66:81], v194, v193 op_sel_hi:[0,0,0]
	v_mov_b32_e32 v0, v219
	s_nop 1
	v_permlane32_swap_b32_e32 v219, v0
	v_add_f32_e32 v219, v219, v0
	v_fma_f32 v209, v209, v221, v219
	v_max_f32_e32 v177, v82, v83
	v_max3_f32 v177, v177, v84, v85
	v_max3_f32 v177, v177, v86, v87
	v_max3_f32 v177, v177, v88, v89
	v_max3_f32 v177, v177, v90, v91
	v_max3_f32 v177, v177, v92, v93
	v_max3_f32 v177, v177, v94, v95
	v_max3_f32 v177, v177, v96, v97
	s_waitcnt vmcnt(0)
	ds_write_b128 v210, v[158:161] offset:8192
	ds_write_b128 v211, v[162:165] offset:24576
	s_waitcnt lgkmcnt(8)
	v_mfma_scale_f32_32x32x64_f8f6f4 v[50:65], v[246:253], v[122:129], v[50:65], v194, v194 op_sel_hi:[0,0,0]
	s_waitcnt lgkmcnt(6)
	v_mfma_scale_f32_32x32x64_f8f6f4 v[34:49], v[246:253], v[114:121], v[34:49], v194, v194 op_sel_hi:[0,0,0]
	s_waitcnt lgkmcnt(0)
	s_barrier
	s_waitcnt lgkmcnt(2)
	v_mfma_scale_f32_32x32x64_f8f6f4 v[18:33], v[246:253], v[106:113], v[18:33], v194, v194 op_sel_hi:[0,0,0]
	global_load_dwordx4 v[158:161], v176, s[18:19]
	global_load_dwordx4 v[162:165], v178, s[16:17]
	v_add_u32_e32 v176, 0x2000, v176
	v_add_u32_e32 v178, 0x20000, v178
	s_waitcnt lgkmcnt(0)
	v_mfma_scale_f32_32x32x64_f8f6f4 v[2:17], v[246:253], v[98:105], v[2:17], v194, v194 op_sel_hi:[0,0,0]
	v_max_f32_e32 v0, v66, v67
	v_max3_f32 v0, v0, v68, v69
	v_max3_f32 v0, v0, v70, v71
	v_max3_f32 v0, v0, v72, v73
	v_max3_f32 v0, v0, v74, v75
	v_max3_f32 v0, v0, v76, v77
	v_max3_f32 v0, v0, v78, v79
	v_max3_f32 v0, v0, v80, v81
	v_max_f32_e32 v177, v177, v0
	v_mov_b32_e32 v0, v177
	v_mov_b32_e32 v218, 1.0
	s_nop 0
	v_permlane32_swap_b32_e32 v177, v0
	v_max_f32_e32 v177, v177, v0
	v_cmp_ge_f32_e32 vcc, s90, v177
	s_cmp_eq_u64 vcc, exec
	s_cbranch_scc0 .Lmla_s5_newmax
; __device__ __forceinline__ void finishSM9(f32x16& p0, f32x16& p1, float alpha, float& l_reg, v8i32& p8) {
; #pragma unroll
;   for (int r = 0; r < 16; ++r) { p0[r] = __builtin_amdgcn_exp2f(p0[r]); p1[r] = __builtin_amdgcn_exp2f(p1[r]); }
;   float ps = 0;
; #pragma unroll
;   for (int r = 0; r < 16; ++r) ps += p0[r];
; #pragma unroll
;   for (int r = 0; r < 16; ++r) ps += p1[r];
;   { auto rr = __builtin_amdgcn_permlane32_swap(__float_as_uint(ps), __float_as_uint(ps), false, false);
;     ps = __uint_as_float(rr[0]) + __uint_as_float(rr[1]); }
;   l_reg = l_reg * alpha + ps;
; #pragma unroll
;   for (int g = 0; g < 4; ++g) {
;     int w = __builtin_amdgcn_cvt_pk_fp8_f32(p0[4 * g], p0[4 * g + 1], 0, false); p8[g] = __builtin_amdgcn_cvt_pk_fp8_f32(p0[4 * g + 2], p0[4 * g + 3], w, true);
;     int u = __builtin_amdgcn_cvt_pk_fp8_f32(p1[4 * g], p1[4 * g + 1], 0, false); p8[4 + g] = __builtin_amdgcn_cvt_pk_fp8_f32(p1[4 * g + 2], p1[4 * g + 3], u, true); }
; }
; __device__ __forceinline__ void pv8(f32x16* o, const char* Vt, const v8i32 p8, int r32, int hi) {
;   const int sw = (r32 >> 2) & 3, a0 = r32 * 64 + (((hi * 2) ^ sw) << 4), a1 = r32 * 64 + (((hi * 2 + 1) ^ sw) << 4);
; #pragma unroll
;   for (int d0 = 0; d0 < 4; ++d0) {
;     const v8i32 vf = cat8(*reinterpret_cast<const v4i32*>(Vt + d0 * 2048 + a0), *reinterpret_cast<const v4i32*>(Vt + d0 * 2048 + a1));
;     o[d0] = __builtin_amdgcn_mfma_scale_f32_32x32x64_f8f6f4(p8, vf, o[d0], 0, 0, 0, 127, 0, 127); }
; }
; __device__ __forceinline__ void qkt9(f32x16& p0, f32x16& p1, const char* Kn, const char* Kr, const v8i32* qf, const float init, int r32, int hi) {
; #pragma unroll
;   for (int r = 0; r < 16; ++r) { p0[r] = init; p1[r] = init; }
; #pragma unroll
;   for (int s = 0; s < 2; ++s) { const int c0 = s * 4 + hi * 2;
;     const v8i32 a0 = cat8(*reinterpret_cast<const v4i32*>(Kn + KN8SW(r32, c0)), *reinterpret_cast<const v4i32*>(Kn + KN8SW(r32, c0 + 1)));
;     const v8i32 a1 = cat8(*reinterpret_cast<const v4i32*>(Kn + 4096 + KN8SW(r32, c0)), *reinterpret_cast<const v4i32*>(Kn + 4096 + KN8SW(r32, c0 + 1)));
;     p0 = __builtin_amdgcn_mfma_scale_f32_32x32x64_f8f6f4(a0, qf[s], p0, 0, 0, 0, 127, 0, 124);
;     p1 = __builtin_amdgcn_mfma_scale_f32_32x32x64_f8f6f4(a1, qf[s], p1, 0, 0, 0, 127, 0, 124); }
;   { const int c0 = hi * 2;
.Lmla_s5_cont:
	s_add_i32 s30, s30, 1
	s_cmpk_lt_u32 s30, 42
	s_cbranch_scc1 .Lmla_stag_loop
	ds_read_b128 v[114:117], v215 offset:24576
	ds_read_b128 v[118:121], v216 offset:24576
	ds_read_b128 v[222:225], v215 offset:28672
	ds_read_b128 v[226:229], v216 offset:28672
	v_exp_f32_e32 v0, v82
	v_exp_f32_e32 v177, v83
	v_exp_f32_e32 v179, v84
	v_exp_f32_e32 v254, v85
	v_add_f32_e32 v219, v0, v177
	v_cvt_pk_fp8_f32 v246, v0, v177
	v_add_f32_e32 v219, v179, v219
	v_add_f32_e32 v219, v254, v219
	v_cvt_pk_fp8_f32 v246, v179, v254 op_sel:[0,0,1]
	s_waitcnt lgkmcnt(2)
	v_mfma_scale_f32_32x32x64_f8f6f4 v[114:129], v[114:121], v[146:153], v[230:245], v194, v193 op_sel_hi:[0,0,0]
	v_exp_f32_e32 v0, v86
	v_exp_f32_e32 v177, v87
	v_exp_f32_e32 v179, v88
	v_exp_f32_e32 v254, v89
	v_add_f32_e32 v219, v0, v219
	v_add_f32_e32 v219, v177, v219
	v_cvt_pk_fp8_f32 v247, v0, v177
	v_add_f32_e32 v219, v179, v219
	v_add_f32_e32 v219, v254, v219
	v_cvt_pk_fp8_f32 v247, v179, v254 op_sel:[0,0,1]
	ds_read_b128 v[82:85], v213 offset:24576
	ds_read_b128 v[86:89], v214 offset:24576
	s_waitcnt lgkmcnt(2)
	v_mfma_scale_f32_32x32x64_f8f6f4 v[98:113], v[222:229], v[146:153], v[230:245], v194, v193 op_sel_hi:[0,0,0]
	ds_read_b128 v[222:225], v213 offset:28672
	ds_read_b128 v[226:229], v214 offset:28672
	v_exp_f32_e32 v0, v90
	v_exp_f32_e32 v177, v91
	v_exp_f32_e32 v179, v92
	v_exp_f32_e32 v254, v93
	v_add_f32_e32 v219, v0, v219
	v_add_f32_e32 v219, v177, v219
	v_cvt_pk_fp8_f32 v248, v0, v177
	v_add_f32_e32 v219, v179, v219
	v_add_f32_e32 v219, v254, v219
	v_cvt_pk_fp8_f32 v248, v179, v254 op_sel:[0,0,1]
	v_exp_f32_e32 v0, v94
	v_exp_f32_e32 v177, v95
	v_exp_f32_e32 v179, v96
	v_exp_f32_e32 v254, v97
	v_add_f32_e32 v219, v0, v219
	v_add_f32_e32 v219, v177, v219
	v_cvt_pk_fp8_f32 v249, v0, v177
	v_add_f32_e32 v219, v179, v219
	v_add_f32_e32 v219, v254, v219
	v_cvt_pk_fp8_f32 v249, v179, v254 op_sel:[0,0,1]
	ds_read_b128 v[90:93], v185 offset:36864
	ds_read_b128 v[94:97], v186 offset:36864
	s_waitcnt lgkmcnt(4)
	v_mfma_scale_f32_32x32x64_f8f6f4 v[114:129], v[82:89], v[138:145], v[114:129], v194, v193 op_sel_hi:[0,0,0]
	v_exp_f32_e32 v0, v66
	v_exp_f32_e32 v177, v67
	v_exp_f32_e32 v179, v68
	v_exp_f32_e32 v254, v69
	v_add_f32_e32 v219, v0, v219
	v_add_f32_e32 v219, v177, v219
	v_cvt_pk_fp8_f32 v250, v0, v177
	v_add_f32_e32 v219, v179, v219
	v_add_f32_e32 v219, v254, v219
	v_cvt_pk_fp8_f32 v250, v179, v254 op_sel:[0,0,1]
	s_waitcnt lgkmcnt(2)
	v_mfma_scale_f32_32x32x64_f8f6f4 v[98:113], v[222:229], v[138:145], v[98:113], v194, v193 op_sel_hi:[0,0,0]
	ds_read_b128 v[222:225], v185 offset:38912
	ds_read_b128 v[226:229], v186 offset:38912
	v_exp_f32_e32 v0, v70
	v_exp_f32_e32 v177, v71
	v_exp_f32_e32 v179, v72
	v_exp_f32_e32 v254, v73
	v_add_f32_e32 v219, v0, v219
	v_add_f32_e32 v219, v177, v219
	v_cvt_pk_fp8_f32 v251, v0, v177
	v_add_f32_e32 v219, v179, v219
	v_add_f32_e32 v219, v254, v219
	v_cvt_pk_fp8_f32 v251, v179, v254 op_sel:[0,0,1]
	v_exp_f32_e32 v0, v74
	v_exp_f32_e32 v177, v75
	v_exp_f32_e32 v179, v76
	v_exp_f32_e32 v254, v77
	v_add_f32_e32 v219, v0, v219
	v_add_f32_e32 v219, v177, v219
	v_cvt_pk_fp8_f32 v252, v0, v177
	v_add_f32_e32 v219, v179, v219
	v_add_f32_e32 v219, v254, v219
	v_cvt_pk_fp8_f32 v252, v179, v254 op_sel:[0,0,1]
	s_waitcnt lgkmcnt(2)
	v_mfma_scale_f32_32x32x64_f8f6f4 v[114:129], v[90:97], v[130:137], v[114:129], v194, v193 op_sel_hi:[0,0,0]
	v_exp_f32_e32 v0, v78
	v_exp_f32_e32 v177, v79
	v_exp_f32_e32 v179, v80
	v_exp_f32_e32 v254, v81
	v_add_f32_e32 v219, v0, v219
	v_add_f32_e32 v219, v177, v219
	v_cvt_pk_fp8_f32 v253, v0, v177
	v_add_f32_e32 v219, v179, v219
	v_add_f32_e32 v219, v254, v219
	v_cvt_pk_fp8_f32 v253, v179, v254 op_sel:[0,0,1]
	ds_read_b128 v[90:93], v185 offset:0
	ds_read_b128 v[94:97], v186 offset:0
	ds_read_b128 v[82:85], v185 offset:2048
	ds_read_b128 v[86:89], v186 offset:2048
	ds_read_b128 v[74:77], v185 offset:4096
	ds_read_b128 v[78:81], v186 offset:4096
	ds_read_b128 v[66:69], v185 offset:6144
	ds_read_b128 v[70:73], v186 offset:6144
	s_waitcnt lgkmcnt(8)
	v_mfma_scale_f32_32x32x64_f8f6f4 v[98:113], v[222:229], v[130:137], v[98:113], v194, v193 op_sel_hi:[0,0,0]
	v_mov_b32_e32 v0, v219
	s_nop 1
	v_permlane32_swap_b32_e32 v219, v0
	v_add_f32_e32 v219, v219, v0
	v_fma_f32 v209, v209, v218, v219
	v_max_f32_e32 v177, v114, v115
	v_max3_f32 v177, v177, v116, v117
	v_max3_f32 v177, v177, v118, v119
	v_max3_f32 v177, v177, v120, v121
	v_max3_f32 v177, v177, v122, v123
	v_max3_f32 v177, v177, v124, v125
	v_max3_f32 v177, v177, v126, v127
	v_max3_f32 v177, v177, v128, v129
	s_waitcnt vmcnt(0)
	ds_write_b128 v210, v[158:161] offset:43008
	ds_write_b128 v211, v[162:165] offset:51200
	s_waitcnt lgkmcnt(8)
	v_mfma_scale_f32_32x32x64_f8f6f4 v[50:65], v[246:253], v[90:97], v[50:65], v194, v194 op_sel_hi:[0,0,0]
	s_waitcnt lgkmcnt(6)
	v_mfma_scale_f32_32x32x64_f8f6f4 v[34:49], v[246:253], v[82:89], v[34:49], v194, v194 op_sel_hi:[0,0,0]
	s_waitcnt lgkmcnt(0)
	s_barrier
	s_waitcnt lgkmcnt(2)
	v_mfma_scale_f32_32x32x64_f8f6f4 v[18:33], v[246:253], v[74:81], v[18:33], v194, v194 op_sel_hi:[0,0,0]
	global_load_dwordx4 v[158:161], v176, s[18:19]
	global_load_dwordx4 v[162:165], v178, s[16:17]
	v_add_u32_e32 v176, 0x2000, v176
	v_add_u32_e32 v178, 0x20000, v178
	s_waitcnt lgkmcnt(0)
	v_mfma_scale_f32_32x32x64_f8f6f4 v[2:17], v[246:253], v[66:73], v[2:17], v194, v194 op_sel_hi:[0,0,0]
	v_max_f32_e32 v0, v98, v99
	v_max3_f32 v0, v0, v100, v101
	v_max3_f32 v0, v0, v102, v103
	v_max3_f32 v0, v0, v104, v105
	v_max3_f32 v0, v0, v106, v107
	v_max3_f32 v0, v0, v108, v109
	v_max3_f32 v0, v0, v110, v111
	v_max3_f32 v0, v0, v112, v113
	v_max_f32_e32 v177, v177, v0
	v_mov_b32_e32 v0, v177
	v_mov_b32_e32 v221, 1.0
	s_nop 0
	v_permlane32_swap_b32_e32 v177, v0
	v_max_f32_e32 v177, v177, v0
	v_cmp_ge_f32_e32 vcc, s90, v177
	s_cmp_eq_u64 vcc, exec
	s_cbranch_scc0 .Lmla_q0_newmax
